# scan: last reduce-scatter group and y store of each chunk deferred behind the next chunk's first LDS read burst
# speedup vs baseline: 1.0218x; 1.0006x over previous
.LBB0_496:
	s_and_b32 s54, s58, 1
	s_waitcnt lgkmcnt(0)
	s_barrier
	s_and_saveexec_b64 s[40:41], s[4:5]
	s_xor_b64 s[52:53], exec, s[40:41]
	s_cbranch_execz .LBB0_498
	s_mov_b32 s11, s10
	s_mov_b32 s15, s14
	s_mov_b32 s35, s34
	s_mov_b32 s37, s36
	s_mov_b32 s43, s42
	s_mov_b32 s45, s44
	s_mul_i32 s40, s54, 0xa000
	s_mul_i32 s41, s54, 0xa00
	s_add_i32 s41, s41, 0x14000
	v_add_u32_e32 v29, s40, v24
	v_add_lshl_u32 v31, v23, v22, 2
	v_mov_b32_e32 v30, s41
	v_add_u32_e32 v31, s41, v31
	v_add_u32_e32 v122, 0x3c0, v31
	v_add_u32_e32 v123, 0x780, v31
	v_add_u32_e32 v124, 0x3c0, v30
	v_add_u32_e32 v125, 0x780, v30
	ds_read_b128 v[44:47], v29 offset:48
	ds_read_b128 v[64:67], v29 offset:1328
	ds_read_b128 v[40:43], v29 offset:32
	ds_read2_b32 v[112:113], v31 offset0:0 offset1:20
	ds_read_b128 v[32:35], v29 offset:0
	ds_read2_b32 v[118:119], v30 offset0:36 offset1:76
	ds_read_b128 v[48:51], v29 offset:64
	ds_read_b128 v[60:63], v29 offset:1312
	ds_read_b128 v[52:55], v29 offset:1280
	ds_read_b128 v[36:39], v29 offset:16
	ds_read_b128 v[68:71], v29 offset:1344
	ds_read_b128 v[56:59], v29 offset:1296
	s_cmp_eq_u32 s58, 0
	s_cbranch_scc1 .Lscan_tail_skip0
	v_add_f32_e32 v206, v144, v145
	v_add_f32_e32 v207, v146, v147
	v_cndmask_b32_e64 v208, v204, v205, s[10:11]
	v_cndmask_b32_e64 v209, v205, v204, s[10:11]
	v_cndmask_b32_e64 v210, v206, v207, s[10:11]
	v_cndmask_b32_e64 v211, v207, v206, s[10:11]
	v_add_f32_dpp v212, v209, v208 quad_perm:[1,0,3,2] row_mask:0xf bank_mask:0xf bound_ctrl:1
	s_nop 0
	v_add_f32_dpp v213, v211, v210 quad_perm:[1,0,3,2] row_mask:0xf bank_mask:0xf bound_ctrl:1
	v_cndmask_b32_e64 v214, v212, v213, s[14:15]
	v_cndmask_b32_e64 v215, v213, v212, s[14:15]
	s_nop 1
	v_add_f32_dpp v216, v215, v214 quad_perm:[2,3,0,1] row_mask:0xf bank_mask:0xf bound_ctrl:1
	s_nop 1
	v_add_f32_dpp v216, v216, v216 row_ror:8 row_mask:0xf bank_mask:0xf bound_ctrl:1
	s_nop 1
	v_add_f32_dpp v216, v216, v216 row_ror:4 row_mask:0xf bank_mask:0xf bound_ctrl:1
	v_cndmask_b32_e64 v28, v28, v216, s[44:45]
	v_add_co_u32_e32 v218, vcc, 0x4cfc000, v12
	s_nop 1
	v_addc_co_u32_e32 v219, vcc, 0, v13, vcc
	global_store_dword v[218:219], v28, off
.Lscan_tail_skip0:
	s_waitcnt lgkmcnt(7)
	v_pk_mul_f32 v[132:133], v[16:17], v[44:45]
	v_pk_mul_f32 v[134:135], v[16:17], v[64:65]
	v_pk_fma_f32 v[132:133], v[18:19], v[46:47], v[132:133]
	v_pk_fma_f32 v[134:135], v[18:19], v[66:67], v[134:135]
	v_pk_mul_f32 v[136:137], v[112:113], v[40:41] op_sel_hi:[0,1]
	v_add_f32_e32 v148, v132, v133
	v_add_f32_e32 v149, v134, v135
	v_pk_mul_f32 v[138:139], v[112:113], v[42:43] op_sel_hi:[0,1]
	v_add_f32_dpp v148, v148, v148 quad_perm:[1,0,3,2] row_mask:0xf bank_mask:0xf bound_ctrl:1
	v_add_f32_dpp v149, v149, v149 quad_perm:[1,0,3,2] row_mask:0xf bank_mask:0xf bound_ctrl:1
	v_pk_fma_f32 v[136:137], v[16:17], v[32:33], v[136:137]
	v_add_f32_dpp v148, v148, v148 quad_perm:[2,3,0,1] row_mask:0xf bank_mask:0xf bound_ctrl:1
	v_add_f32_dpp v149, v149, v149 quad_perm:[2,3,0,1] row_mask:0xf bank_mask:0xf bound_ctrl:1
	v_pk_fma_f32 v[138:139], v[18:19], v[34:35], v[138:139]
	v_add_f32_dpp v148, v148, v148 row_half_mirror row_mask:0xf bank_mask:0xf bound_ctrl:1
	v_add_f32_dpp v149, v149, v149 row_half_mirror row_mask:0xf bank_mask:0xf bound_ctrl:1
	ds_read_b128 v[84:87], v29 offset:2608
	ds_read_b128 v[104:107], v29 offset:3888
	ds_read_b128 v[80:83], v29 offset:2592
	ds_read2_b32 v[114:115], v31 offset0:40 offset1:60
	ds_read_b128 v[72:75], v29 offset:2560
	ds_read_b128 v[88:91], v29 offset:2624
	ds_read_b128 v[100:103], v29 offset:3872
	ds_read_b128 v[92:95], v29 offset:3840
	ds_read_b128 v[76:79], v29 offset:2576
	ds_read_b128 v[108:111], v29 offset:3904
	ds_read_b128 v[96:99], v29 offset:3856
	s_waitcnt lgkmcnt(11)
	v_pk_mul_f32 v[140:141], v[112:113], v[60:61] op_sel:[1,0] op_sel_hi:[1,1]
	v_add_f32_dpp v148, v148, v148 row_mirror row_mask:0xf bank_mask:0xf bound_ctrl:1
	v_add_f32_dpp v149, v149, v149 row_mirror row_mask:0xf bank_mask:0xf bound_ctrl:1
	v_pk_mul_f32 v[142:143], v[112:113], v[62:63] op_sel:[1,0] op_sel_hi:[1,1]
	v_fmac_f32_e32 v149, v112, v118
	v_pk_fma_f32 v[16:17], v[48:49], v[148:149], v[136:137] op_sel_hi:[1,0,1]
	v_pk_fma_f32 v[18:19], v[50:51], v[148:149], v[138:139] op_sel_hi:[1,0,1]
	v_pk_fma_f32 v[140:141], v[16:17], v[52:53], v[140:141]
	v_pk_mul_f32 v[144:145], v[16:17], v[36:37]
	v_pk_fma_f32 v[142:143], v[18:19], v[54:55], v[142:143]
	v_pk_fma_f32 v[144:145], v[18:19], v[38:39], v[144:145]
	v_pk_fma_f32 v[16:17], v[68:69], v[148:149], v[140:141] op_sel:[0,1,0] op_sel_hi:[1,1,1]
	v_pk_fma_f32 v[18:19], v[70:71], v[148:149], v[142:143] op_sel:[0,1,0] op_sel_hi:[1,1,1]
	v_pk_mul_f32 v[146:147], v[16:17], v[56:57]
	v_pk_fma_f32 v[146:147], v[18:19], v[58:59], v[146:147]
	s_waitcnt lgkmcnt(6)
	v_pk_mul_f32 v[132:133], v[16:17], v[84:85]
	v_pk_mul_f32 v[134:135], v[16:17], v[104:105]
	v_add_f32_e32 v200, v144, v145
	v_pk_fma_f32 v[132:133], v[18:19], v[86:87], v[132:133]
	v_pk_fma_f32 v[134:135], v[18:19], v[106:107], v[134:135]
	v_add_f32_e32 v201, v146, v147
	v_pk_mul_f32 v[136:137], v[114:115], v[80:81] op_sel_hi:[0,1]
	v_add_f32_e32 v148, v132, v133
	v_add_f32_e32 v149, v134, v135
	v_pk_mul_f32 v[138:139], v[114:115], v[82:83] op_sel_hi:[0,1]
	v_add_f32_dpp v148, v148, v148 quad_perm:[1,0,3,2] row_mask:0xf bank_mask:0xf bound_ctrl:1
	v_add_f32_dpp v149, v149, v149 quad_perm:[1,0,3,2] row_mask:0xf bank_mask:0xf bound_ctrl:1
	v_pk_fma_f32 v[136:137], v[16:17], v[72:73], v[136:137]
	v_add_f32_dpp v148, v148, v148 quad_perm:[2,3,0,1] row_mask:0xf bank_mask:0xf bound_ctrl:1
	v_add_f32_dpp v149, v149, v149 quad_perm:[2,3,0,1] row_mask:0xf bank_mask:0xf bound_ctrl:1
	v_pk_fma_f32 v[138:139], v[18:19], v[74:75], v[138:139]
	v_add_f32_dpp v148, v148, v148 row_half_mirror row_mask:0xf bank_mask:0xf bound_ctrl:1
	v_add_f32_dpp v149, v149, v149 row_half_mirror row_mask:0xf bank_mask:0xf bound_ctrl:1
	ds_read_b128 v[172:175], v29 offset:5168
	ds_read_b128 v[192:195], v29 offset:6448
	ds_read_b128 v[168:171], v29 offset:5152
	ds_read2_b32 v[116:117], v31 offset0:80 offset1:100
	ds_read_b128 v[160:163], v29 offset:5120
	ds_read2_b32 v[120:121], v30 offset0:116 offset1:156
	ds_read_b128 v[176:179], v29 offset:5184
	ds_read_b128 v[188:191], v29 offset:6432
	ds_read_b128 v[180:183], v29 offset:6400
	ds_read_b128 v[164:167], v29 offset:5136
	ds_read_b128 v[196:199], v29 offset:6464
	ds_read_b128 v[184:187], v29 offset:6416
	s_waitcnt lgkmcnt(12)
	v_pk_mul_f32 v[140:141], v[114:115], v[100:101] op_sel:[1,0] op_sel_hi:[1,1]
	v_add_f32_dpp v148, v148, v148 row_mirror row_mask:0xf bank_mask:0xf bound_ctrl:1
	v_add_f32_dpp v149, v149, v149 row_mirror row_mask:0xf bank_mask:0xf bound_ctrl:1
	v_pk_mul_f32 v[142:143], v[114:115], v[102:103] op_sel:[1,0] op_sel_hi:[1,1]
	v_fmac_f32_e32 v149, v114, v119
	v_pk_fma_f32 v[16:17], v[88:89], v[148:149], v[136:137] op_sel_hi:[1,0,1]
	v_pk_fma_f32 v[18:19], v[90:91], v[148:149], v[138:139] op_sel_hi:[1,0,1]
	v_pk_fma_f32 v[140:141], v[16:17], v[92:93], v[140:141]
	v_pk_mul_f32 v[144:145], v[16:17], v[76:77]
	v_pk_fma_f32 v[142:143], v[18:19], v[94:95], v[142:143]
	v_pk_fma_f32 v[144:145], v[18:19], v[78:79], v[144:145]
	v_pk_fma_f32 v[16:17], v[108:109], v[148:149], v[140:141] op_sel:[0,1,0] op_sel_hi:[1,1,1]
	v_pk_fma_f32 v[18:19], v[110:111], v[148:149], v[142:143] op_sel:[0,1,0] op_sel_hi:[1,1,1]
	v_pk_mul_f32 v[146:147], v[16:17], v[96:97]
	v_pk_fma_f32 v[146:147], v[18:19], v[98:99], v[146:147]
	s_waitcnt lgkmcnt(7)
	v_pk_mul_f32 v[132:133], v[16:17], v[172:173]
	v_pk_mul_f32 v[134:135], v[16:17], v[192:193]
	v_add_f32_e32 v202, v144, v145
	v_pk_fma_f32 v[132:133], v[18:19], v[174:175], v[132:133]
	v_pk_fma_f32 v[134:135], v[18:19], v[194:195], v[134:135]
	v_add_f32_e32 v203, v146, v147
	v_pk_mul_f32 v[136:137], v[116:117], v[168:169] op_sel_hi:[0,1]
	v_add_f32_e32 v148, v132, v133
	v_cndmask_b32_e64 v208, v200, v201, s[10:11]
	v_add_f32_e32 v149, v134, v135
	v_pk_mul_f32 v[138:139], v[116:117], v[170:171] op_sel_hi:[0,1]
	v_cndmask_b32_e64 v209, v201, v200, s[10:11]
	v_add_f32_dpp v148, v148, v148 quad_perm:[1,0,3,2] row_mask:0xf bank_mask:0xf bound_ctrl:1
	v_add_f32_dpp v149, v149, v149 quad_perm:[1,0,3,2] row_mask:0xf bank_mask:0xf bound_ctrl:1
	v_cndmask_b32_e64 v210, v202, v203, s[10:11]
	v_pk_fma_f32 v[136:137], v[16:17], v[160:161], v[136:137]
	v_add_f32_dpp v148, v148, v148 quad_perm:[2,3,0,1] row_mask:0xf bank_mask:0xf bound_ctrl:1
	v_cndmask_b32_e64 v211, v203, v202, s[10:11]
	v_add_f32_dpp v149, v149, v149 quad_perm:[2,3,0,1] row_mask:0xf bank_mask:0xf bound_ctrl:1
	v_pk_fma_f32 v[138:139], v[18:19], v[162:163], v[138:139]
	v_add_f32_dpp v212, v209, v208 quad_perm:[1,0,3,2] row_mask:0xf bank_mask:0xf bound_ctrl:1
	v_add_f32_dpp v148, v148, v148 row_half_mirror row_mask:0xf bank_mask:0xf bound_ctrl:1
	v_add_f32_dpp v149, v149, v149 row_half_mirror row_mask:0xf bank_mask:0xf bound_ctrl:1
	v_add_f32_dpp v213, v211, v210 quad_perm:[1,0,3,2] row_mask:0xf bank_mask:0xf bound_ctrl:1
	ds_read_b128 v[44:47], v29 offset:7728
	ds_read_b128 v[64:67], v29 offset:9008
	ds_read_b128 v[40:43], v29 offset:7712
	ds_read2_b32 v[112:113], v31 offset0:120 offset1:140
	ds_read_b128 v[32:35], v29 offset:7680
	ds_read_b128 v[48:51], v29 offset:7744
	ds_read_b128 v[60:63], v29 offset:8992
	ds_read_b128 v[52:55], v29 offset:8960
	ds_read_b128 v[36:39], v29 offset:7696
	ds_read_b128 v[68:71], v29 offset:9024
	ds_read_b128 v[56:59], v29 offset:8976
	s_waitcnt lgkmcnt(11)
	v_pk_mul_f32 v[140:141], v[116:117], v[188:189] op_sel:[1,0] op_sel_hi:[1,1]
	v_cndmask_b32_e64 v214, v212, v213, s[14:15]
	v_add_f32_dpp v148, v148, v148 row_mirror row_mask:0xf bank_mask:0xf bound_ctrl:1
	v_add_f32_dpp v149, v149, v149 row_mirror row_mask:0xf bank_mask:0xf bound_ctrl:1
	v_cndmask_b32_e64 v215, v213, v212, s[14:15]
	v_pk_mul_f32 v[142:143], v[116:117], v[190:191] op_sel:[1,0] op_sel_hi:[1,1]
	v_fmac_f32_e32 v149, v116, v120
	v_add_f32_dpp v216, v215, v214 quad_perm:[2,3,0,1] row_mask:0xf bank_mask:0xf bound_ctrl:1
	v_pk_fma_f32 v[16:17], v[176:177], v[148:149], v[136:137] op_sel_hi:[1,0,1]
	v_pk_fma_f32 v[18:19], v[178:179], v[148:149], v[138:139] op_sel_hi:[1,0,1]
	v_add_f32_dpp v216, v216, v216 row_ror:8 row_mask:0xf bank_mask:0xf bound_ctrl:1
	v_pk_fma_f32 v[140:141], v[16:17], v[180:181], v[140:141]
	v_pk_mul_f32 v[144:145], v[16:17], v[164:165]
	v_add_f32_dpp v216, v216, v216 row_ror:4 row_mask:0xf bank_mask:0xf bound_ctrl:1
	v_pk_fma_f32 v[142:143], v[18:19], v[182:183], v[142:143]
	v_pk_fma_f32 v[144:145], v[18:19], v[166:167], v[144:145]
	v_cndmask_b32_e64 v28, v28, v216, s[34:35]
	v_pk_fma_f32 v[16:17], v[196:197], v[148:149], v[140:141] op_sel:[0,1,0] op_sel_hi:[1,1,1]
	v_pk_fma_f32 v[18:19], v[198:199], v[148:149], v[142:143] op_sel:[0,1,0] op_sel_hi:[1,1,1]
	v_pk_mul_f32 v[146:147], v[16:17], v[184:185]
	v_pk_fma_f32 v[146:147], v[18:19], v[186:187], v[146:147]
	s_waitcnt lgkmcnt(6)
	v_pk_mul_f32 v[132:133], v[16:17], v[44:45]
	v_pk_mul_f32 v[134:135], v[16:17], v[64:65]
	v_add_f32_e32 v204, v144, v145
	v_pk_fma_f32 v[132:133], v[18:19], v[46:47], v[132:133]
	v_pk_fma_f32 v[134:135], v[18:19], v[66:67], v[134:135]
	v_add_f32_e32 v205, v146, v147
	v_pk_mul_f32 v[136:137], v[112:113], v[40:41] op_sel_hi:[0,1]
	v_add_f32_e32 v148, v132, v133
	v_add_f32_e32 v149, v134, v135
	v_pk_mul_f32 v[138:139], v[112:113], v[42:43] op_sel_hi:[0,1]
	v_add_f32_dpp v148, v148, v148 quad_perm:[1,0,3,2] row_mask:0xf bank_mask:0xf bound_ctrl:1
	v_add_f32_dpp v149, v149, v149 quad_perm:[1,0,3,2] row_mask:0xf bank_mask:0xf bound_ctrl:1
	v_pk_fma_f32 v[136:137], v[16:17], v[32:33], v[136:137]
	v_add_f32_dpp v148, v148, v148 quad_perm:[2,3,0,1] row_mask:0xf bank_mask:0xf bound_ctrl:1
	v_add_f32_dpp v149, v149, v149 quad_perm:[2,3,0,1] row_mask:0xf bank_mask:0xf bound_ctrl:1
	v_pk_fma_f32 v[138:139], v[18:19], v[34:35], v[138:139]
	v_add_f32_dpp v148, v148, v148 row_half_mirror row_mask:0xf bank_mask:0xf bound_ctrl:1
	v_add_f32_dpp v149, v149, v149 row_half_mirror row_mask:0xf bank_mask:0xf bound_ctrl:1
	ds_read_b128 v[84:87], v29 offset:10288
	ds_read_b128 v[104:107], v29 offset:11568
	ds_read_b128 v[80:83], v29 offset:10272
	ds_read2_b32 v[114:115], v31 offset0:160 offset1:180
	ds_read_b128 v[72:75], v29 offset:10240
	ds_read2_b32 v[118:119], v30 offset0:196 offset1:236
	ds_read_b128 v[88:91], v29 offset:10304
	ds_read_b128 v[100:103], v29 offset:11552
	ds_read_b128 v[92:95], v29 offset:11520
	ds_read_b128 v[76:79], v29 offset:10256
	ds_read_b128 v[108:111], v29 offset:11584
	ds_read_b128 v[96:99], v29 offset:11536
	s_waitcnt lgkmcnt(12)
	v_pk_mul_f32 v[140:141], v[112:113], v[60:61] op_sel:[1,0] op_sel_hi:[1,1]
	v_add_f32_dpp v148, v148, v148 row_mirror row_mask:0xf bank_mask:0xf bound_ctrl:1
	v_add_f32_dpp v149, v149, v149 row_mirror row_mask:0xf bank_mask:0xf bound_ctrl:1
	v_pk_mul_f32 v[142:143], v[112:113], v[62:63] op_sel:[1,0] op_sel_hi:[1,1]
	v_fmac_f32_e32 v149, v112, v121
	v_pk_fma_f32 v[16:17], v[48:49], v[148:149], v[136:137] op_sel_hi:[1,0,1]
	v_pk_fma_f32 v[18:19], v[50:51], v[148:149], v[138:139] op_sel_hi:[1,0,1]
	v_pk_fma_f32 v[140:141], v[16:17], v[52:53], v[140:141]
	v_pk_mul_f32 v[144:145], v[16:17], v[36:37]
	v_pk_fma_f32 v[142:143], v[18:19], v[54:55], v[142:143]
	v_pk_fma_f32 v[144:145], v[18:19], v[38:39], v[144:145]
	v_pk_fma_f32 v[16:17], v[68:69], v[148:149], v[140:141] op_sel:[0,1,0] op_sel_hi:[1,1,1]
	v_pk_fma_f32 v[18:19], v[70:71], v[148:149], v[142:143] op_sel:[0,1,0] op_sel_hi:[1,1,1]
	v_pk_mul_f32 v[146:147], v[16:17], v[56:57]
	v_pk_fma_f32 v[146:147], v[18:19], v[58:59], v[146:147]
	s_waitcnt lgkmcnt(7)
	v_pk_mul_f32 v[132:133], v[16:17], v[84:85]
	v_pk_mul_f32 v[134:135], v[16:17], v[104:105]
	v_add_f32_e32 v206, v144, v145
	v_pk_fma_f32 v[132:133], v[18:19], v[86:87], v[132:133]
	v_pk_fma_f32 v[134:135], v[18:19], v[106:107], v[134:135]
	v_add_f32_e32 v207, v146, v147
	v_pk_mul_f32 v[136:137], v[114:115], v[80:81] op_sel_hi:[0,1]
	v_add_f32_e32 v148, v132, v133
	v_cndmask_b32_e64 v208, v204, v205, s[10:11]
	v_add_f32_e32 v149, v134, v135
	v_pk_mul_f32 v[138:139], v[114:115], v[82:83] op_sel_hi:[0,1]
	v_cndmask_b32_e64 v209, v205, v204, s[10:11]
	v_add_f32_dpp v148, v148, v148 quad_perm:[1,0,3,2] row_mask:0xf bank_mask:0xf bound_ctrl:1
	v_add_f32_dpp v149, v149, v149 quad_perm:[1,0,3,2] row_mask:0xf bank_mask:0xf bound_ctrl:1
	v_cndmask_b32_e64 v210, v206, v207, s[10:11]
	v_pk_fma_f32 v[136:137], v[16:17], v[72:73], v[136:137]
	v_add_f32_dpp v148, v148, v148 quad_perm:[2,3,0,1] row_mask:0xf bank_mask:0xf bound_ctrl:1
	v_cndmask_b32_e64 v211, v207, v206, s[10:11]
	v_add_f32_dpp v149, v149, v149 quad_perm:[2,3,0,1] row_mask:0xf bank_mask:0xf bound_ctrl:1
	v_pk_fma_f32 v[138:139], v[18:19], v[74:75], v[138:139]
	v_add_f32_dpp v212, v209, v208 quad_perm:[1,0,3,2] row_mask:0xf bank_mask:0xf bound_ctrl:1
	v_add_f32_dpp v148, v148, v148 row_half_mirror row_mask:0xf bank_mask:0xf bound_ctrl:1
	v_add_f32_dpp v149, v149, v149 row_half_mirror row_mask:0xf bank_mask:0xf bound_ctrl:1
	v_add_f32_dpp v213, v211, v210 quad_perm:[1,0,3,2] row_mask:0xf bank_mask:0xf bound_ctrl:1
	ds_read_b128 v[172:175], v29 offset:12848
	ds_read_b128 v[192:195], v29 offset:14128
	ds_read_b128 v[168:171], v29 offset:12832
	ds_read2_b32 v[116:117], v31 offset0:200 offset1:220
	ds_read_b128 v[160:163], v29 offset:12800
	ds_read_b128 v[176:179], v29 offset:12864
	ds_read_b128 v[188:191], v29 offset:14112
	ds_read_b128 v[180:183], v29 offset:14080
	ds_read_b128 v[164:167], v29 offset:12816
	ds_read_b128 v[196:199], v29 offset:14144
	ds_read_b128 v[184:187], v29 offset:14096
	s_waitcnt lgkmcnt(11)
	v_pk_mul_f32 v[140:141], v[114:115], v[100:101] op_sel:[1,0] op_sel_hi:[1,1]
	v_cndmask_b32_e64 v214, v212, v213, s[14:15]
	v_add_f32_dpp v148, v148, v148 row_mirror row_mask:0xf bank_mask:0xf bound_ctrl:1
	v_add_f32_dpp v149, v149, v149 row_mirror row_mask:0xf bank_mask:0xf bound_ctrl:1
	v_cndmask_b32_e64 v215, v213, v212, s[14:15]
	v_pk_mul_f32 v[142:143], v[114:115], v[102:103] op_sel:[1,0] op_sel_hi:[1,1]
	v_fmac_f32_e32 v149, v114, v118
	v_add_f32_dpp v216, v215, v214 quad_perm:[2,3,0,1] row_mask:0xf bank_mask:0xf bound_ctrl:1
	v_pk_fma_f32 v[16:17], v[88:89], v[148:149], v[136:137] op_sel_hi:[1,0,1]
	v_pk_fma_f32 v[18:19], v[90:91], v[148:149], v[138:139] op_sel_hi:[1,0,1]
	v_add_f32_dpp v216, v216, v216 row_ror:8 row_mask:0xf bank_mask:0xf bound_ctrl:1
	v_pk_fma_f32 v[140:141], v[16:17], v[92:93], v[140:141]
	v_pk_mul_f32 v[144:145], v[16:17], v[76:77]
	v_add_f32_dpp v216, v216, v216 row_ror:4 row_mask:0xf bank_mask:0xf bound_ctrl:1
	v_pk_fma_f32 v[142:143], v[18:19], v[94:95], v[142:143]
	v_pk_fma_f32 v[144:145], v[18:19], v[78:79], v[144:145]
	v_cndmask_b32_e64 v28, v28, v216, s[36:37]
	v_pk_fma_f32 v[16:17], v[108:109], v[148:149], v[140:141] op_sel:[0,1,0] op_sel_hi:[1,1,1]
	v_pk_fma_f32 v[18:19], v[110:111], v[148:149], v[142:143] op_sel:[0,1,0] op_sel_hi:[1,1,1]
	v_pk_mul_f32 v[146:147], v[16:17], v[96:97]
	v_pk_fma_f32 v[146:147], v[18:19], v[98:99], v[146:147]
	s_waitcnt lgkmcnt(6)
	v_pk_mul_f32 v[132:133], v[16:17], v[172:173]
	v_pk_mul_f32 v[134:135], v[16:17], v[192:193]
	v_add_f32_e32 v200, v144, v145
	v_pk_fma_f32 v[132:133], v[18:19], v[174:175], v[132:133]
	v_pk_fma_f32 v[134:135], v[18:19], v[194:195], v[134:135]
	v_add_f32_e32 v201, v146, v147
	v_pk_mul_f32 v[136:137], v[116:117], v[168:169] op_sel_hi:[0,1]
	v_add_f32_e32 v148, v132, v133
	v_add_f32_e32 v149, v134, v135
	v_pk_mul_f32 v[138:139], v[116:117], v[170:171] op_sel_hi:[0,1]
	v_add_f32_dpp v148, v148, v148 quad_perm:[1,0,3,2] row_mask:0xf bank_mask:0xf bound_ctrl:1
	v_add_f32_dpp v149, v149, v149 quad_perm:[1,0,3,2] row_mask:0xf bank_mask:0xf bound_ctrl:1
	v_pk_fma_f32 v[136:137], v[16:17], v[160:161], v[136:137]
	v_add_f32_dpp v148, v148, v148 quad_perm:[2,3,0,1] row_mask:0xf bank_mask:0xf bound_ctrl:1
	v_add_f32_dpp v149, v149, v149 quad_perm:[2,3,0,1] row_mask:0xf bank_mask:0xf bound_ctrl:1
	v_pk_fma_f32 v[138:139], v[18:19], v[162:163], v[138:139]
	v_add_f32_dpp v148, v148, v148 row_half_mirror row_mask:0xf bank_mask:0xf bound_ctrl:1
	v_add_f32_dpp v149, v149, v149 row_half_mirror row_mask:0xf bank_mask:0xf bound_ctrl:1
	ds_read_b128 v[44:47], v29 offset:15408
	ds_read_b128 v[64:67], v29 offset:16688
	ds_read_b128 v[40:43], v29 offset:15392
	ds_read2_b32 v[112:113], v122 offset0:0 offset1:20
	ds_read_b128 v[32:35], v29 offset:15360
	ds_read2_b32 v[120:121], v124 offset0:36 offset1:76
	ds_read_b128 v[48:51], v29 offset:15424
	ds_read_b128 v[60:63], v29 offset:16672
	ds_read_b128 v[52:55], v29 offset:16640
	ds_read_b128 v[36:39], v29 offset:15376
	ds_read_b128 v[68:71], v29 offset:16704
	ds_read_b128 v[56:59], v29 offset:16656
	s_waitcnt lgkmcnt(12)
	v_pk_mul_f32 v[140:141], v[116:117], v[188:189] op_sel:[1,0] op_sel_hi:[1,1]
	v_add_f32_dpp v148, v148, v148 row_mirror row_mask:0xf bank_mask:0xf bound_ctrl:1
	v_add_f32_dpp v149, v149, v149 row_mirror row_mask:0xf bank_mask:0xf bound_ctrl:1
	v_pk_mul_f32 v[142:143], v[116:117], v[190:191] op_sel:[1,0] op_sel_hi:[1,1]
	v_fmac_f32_e32 v149, v116, v119
	v_pk_fma_f32 v[16:17], v[176:177], v[148:149], v[136:137] op_sel_hi:[1,0,1]
	v_pk_fma_f32 v[18:19], v[178:179], v[148:149], v[138:139] op_sel_hi:[1,0,1]
	v_pk_fma_f32 v[140:141], v[16:17], v[180:181], v[140:141]
	v_pk_mul_f32 v[144:145], v[16:17], v[164:165]
	v_pk_fma_f32 v[142:143], v[18:19], v[182:183], v[142:143]
	v_pk_fma_f32 v[144:145], v[18:19], v[166:167], v[144:145]
	v_pk_fma_f32 v[16:17], v[196:197], v[148:149], v[140:141] op_sel:[0,1,0] op_sel_hi:[1,1,1]
	v_pk_fma_f32 v[18:19], v[198:199], v[148:149], v[142:143] op_sel:[0,1,0] op_sel_hi:[1,1,1]
	v_pk_mul_f32 v[146:147], v[16:17], v[184:185]
	v_pk_fma_f32 v[146:147], v[18:19], v[186:187], v[146:147]
	s_waitcnt lgkmcnt(7)
	v_pk_mul_f32 v[132:133], v[16:17], v[44:45]
	v_pk_mul_f32 v[134:135], v[16:17], v[64:65]
	v_add_f32_e32 v202, v144, v145
	v_pk_fma_f32 v[132:133], v[18:19], v[46:47], v[132:133]
	v_pk_fma_f32 v[134:135], v[18:19], v[66:67], v[134:135]
	v_add_f32_e32 v203, v146, v147
	v_pk_mul_f32 v[136:137], v[112:113], v[40:41] op_sel_hi:[0,1]
	v_add_f32_e32 v148, v132, v133
	v_cndmask_b32_e64 v208, v200, v201, s[10:11]
	v_add_f32_e32 v149, v134, v135
	v_pk_mul_f32 v[138:139], v[112:113], v[42:43] op_sel_hi:[0,1]
	v_cndmask_b32_e64 v209, v201, v200, s[10:11]
	v_add_f32_dpp v148, v148, v148 quad_perm:[1,0,3,2] row_mask:0xf bank_mask:0xf bound_ctrl:1
	v_add_f32_dpp v149, v149, v149 quad_perm:[1,0,3,2] row_mask:0xf bank_mask:0xf bound_ctrl:1
	v_cndmask_b32_e64 v210, v202, v203, s[10:11]
	v_pk_fma_f32 v[136:137], v[16:17], v[32:33], v[136:137]
	v_add_f32_dpp v148, v148, v148 quad_perm:[2,3,0,1] row_mask:0xf bank_mask:0xf bound_ctrl:1
	v_cndmask_b32_e64 v211, v203, v202, s[10:11]
	v_add_f32_dpp v149, v149, v149 quad_perm:[2,3,0,1] row_mask:0xf bank_mask:0xf bound_ctrl:1
	v_pk_fma_f32 v[138:139], v[18:19], v[34:35], v[138:139]
	v_add_f32_dpp v212, v209, v208 quad_perm:[1,0,3,2] row_mask:0xf bank_mask:0xf bound_ctrl:1
	v_add_f32_dpp v148, v148, v148 row_half_mirror row_mask:0xf bank_mask:0xf bound_ctrl:1
	v_add_f32_dpp v149, v149, v149 row_half_mirror row_mask:0xf bank_mask:0xf bound_ctrl:1
	v_add_f32_dpp v213, v211, v210 quad_perm:[1,0,3,2] row_mask:0xf bank_mask:0xf bound_ctrl:1
	ds_read_b128 v[84:87], v29 offset:17968
	ds_read_b128 v[104:107], v29 offset:19248
	ds_read_b128 v[80:83], v29 offset:17952
	ds_read2_b32 v[114:115], v122 offset0:40 offset1:60
	ds_read_b128 v[72:75], v29 offset:17920
	ds_read_b128 v[88:91], v29 offset:17984
	ds_read_b128 v[100:103], v29 offset:19232
	ds_read_b128 v[92:95], v29 offset:19200
	ds_read_b128 v[76:79], v29 offset:17936
	ds_read_b128 v[108:111], v29 offset:19264
	ds_read_b128 v[96:99], v29 offset:19216
	s_waitcnt lgkmcnt(11)
	v_pk_mul_f32 v[140:141], v[112:113], v[60:61] op_sel:[1,0] op_sel_hi:[1,1]
	v_cndmask_b32_e64 v214, v212, v213, s[14:15]
	v_add_f32_dpp v148, v148, v148 row_mirror row_mask:0xf bank_mask:0xf bound_ctrl:1
	v_add_f32_dpp v149, v149, v149 row_mirror row_mask:0xf bank_mask:0xf bound_ctrl:1
	v_cndmask_b32_e64 v215, v213, v212, s[14:15]
	v_pk_mul_f32 v[142:143], v[112:113], v[62:63] op_sel:[1,0] op_sel_hi:[1,1]
	v_fmac_f32_e32 v149, v112, v120
	v_add_f32_dpp v216, v215, v214 quad_perm:[2,3,0,1] row_mask:0xf bank_mask:0xf bound_ctrl:1
	v_pk_fma_f32 v[16:17], v[48:49], v[148:149], v[136:137] op_sel_hi:[1,0,1]
	v_pk_fma_f32 v[18:19], v[50:51], v[148:149], v[138:139] op_sel_hi:[1,0,1]
	v_add_f32_dpp v216, v216, v216 row_ror:8 row_mask:0xf bank_mask:0xf bound_ctrl:1
	v_pk_fma_f32 v[140:141], v[16:17], v[52:53], v[140:141]
	v_pk_mul_f32 v[144:145], v[16:17], v[36:37]
	v_add_f32_dpp v216, v216, v216 row_ror:4 row_mask:0xf bank_mask:0xf bound_ctrl:1
	v_pk_fma_f32 v[142:143], v[18:19], v[54:55], v[142:143]
	v_pk_fma_f32 v[144:145], v[18:19], v[38:39], v[144:145]
	v_cndmask_b32_e64 v28, v28, v216, s[42:43]
	v_pk_fma_f32 v[16:17], v[68:69], v[148:149], v[140:141] op_sel:[0,1,0] op_sel_hi:[1,1,1]
	v_pk_fma_f32 v[18:19], v[70:71], v[148:149], v[142:143] op_sel:[0,1,0] op_sel_hi:[1,1,1]
	v_pk_mul_f32 v[146:147], v[16:17], v[56:57]
	v_pk_fma_f32 v[146:147], v[18:19], v[58:59], v[146:147]
	s_waitcnt lgkmcnt(6)
	v_pk_mul_f32 v[132:133], v[16:17], v[84:85]
	v_pk_mul_f32 v[134:135], v[16:17], v[104:105]
	v_add_f32_e32 v204, v144, v145
	v_pk_fma_f32 v[132:133], v[18:19], v[86:87], v[132:133]
	v_pk_fma_f32 v[134:135], v[18:19], v[106:107], v[134:135]
	v_add_f32_e32 v205, v146, v147
	v_pk_mul_f32 v[136:137], v[114:115], v[80:81] op_sel_hi:[0,1]
	v_add_f32_e32 v148, v132, v133
	v_add_f32_e32 v149, v134, v135
	v_pk_mul_f32 v[138:139], v[114:115], v[82:83] op_sel_hi:[0,1]
	v_add_f32_dpp v148, v148, v148 quad_perm:[1,0,3,2] row_mask:0xf bank_mask:0xf bound_ctrl:1
	v_add_f32_dpp v149, v149, v149 quad_perm:[1,0,3,2] row_mask:0xf bank_mask:0xf bound_ctrl:1
	v_pk_fma_f32 v[136:137], v[16:17], v[72:73], v[136:137]
	v_add_f32_dpp v148, v148, v148 quad_perm:[2,3,0,1] row_mask:0xf bank_mask:0xf bound_ctrl:1
	v_add_f32_dpp v149, v149, v149 quad_perm:[2,3,0,1] row_mask:0xf bank_mask:0xf bound_ctrl:1
	v_pk_fma_f32 v[138:139], v[18:19], v[74:75], v[138:139]
	v_add_f32_dpp v148, v148, v148 row_half_mirror row_mask:0xf bank_mask:0xf bound_ctrl:1
	v_add_f32_dpp v149, v149, v149 row_half_mirror row_mask:0xf bank_mask:0xf bound_ctrl:1
	ds_read_b128 v[172:175], v29 offset:20528
	ds_read_b128 v[192:195], v29 offset:21808
	ds_read_b128 v[168:171], v29 offset:20512
	ds_read2_b32 v[116:117], v122 offset0:80 offset1:100
	ds_read_b128 v[160:163], v29 offset:20480
	ds_read2_b32 v[118:119], v124 offset0:116 offset1:156
	ds_read_b128 v[176:179], v29 offset:20544
	ds_read_b128 v[188:191], v29 offset:21792
	ds_read_b128 v[180:183], v29 offset:21760
	ds_read_b128 v[164:167], v29 offset:20496
	ds_read_b128 v[196:199], v29 offset:21824
	ds_read_b128 v[184:187], v29 offset:21776
	s_waitcnt lgkmcnt(12)
	v_pk_mul_f32 v[140:141], v[114:115], v[100:101] op_sel:[1,0] op_sel_hi:[1,1]
	v_add_f32_dpp v148, v148, v148 row_mirror row_mask:0xf bank_mask:0xf bound_ctrl:1
	v_add_f32_dpp v149, v149, v149 row_mirror row_mask:0xf bank_mask:0xf bound_ctrl:1
	v_pk_mul_f32 v[142:143], v[114:115], v[102:103] op_sel:[1,0] op_sel_hi:[1,1]
	v_fmac_f32_e32 v149, v114, v121
	v_pk_fma_f32 v[16:17], v[88:89], v[148:149], v[136:137] op_sel_hi:[1,0,1]
	v_pk_fma_f32 v[18:19], v[90:91], v[148:149], v[138:139] op_sel_hi:[1,0,1]
	v_pk_fma_f32 v[140:141], v[16:17], v[92:93], v[140:141]
	v_pk_mul_f32 v[144:145], v[16:17], v[76:77]
	v_pk_fma_f32 v[142:143], v[18:19], v[94:95], v[142:143]
	v_pk_fma_f32 v[144:145], v[18:19], v[78:79], v[144:145]
	v_pk_fma_f32 v[16:17], v[108:109], v[148:149], v[140:141] op_sel:[0,1,0] op_sel_hi:[1,1,1]
	v_pk_fma_f32 v[18:19], v[110:111], v[148:149], v[142:143] op_sel:[0,1,0] op_sel_hi:[1,1,1]
	v_pk_mul_f32 v[146:147], v[16:17], v[96:97]
	v_pk_fma_f32 v[146:147], v[18:19], v[98:99], v[146:147]
	s_waitcnt lgkmcnt(7)
	v_pk_mul_f32 v[132:133], v[16:17], v[172:173]
	v_pk_mul_f32 v[134:135], v[16:17], v[192:193]
	v_add_f32_e32 v206, v144, v145
	v_pk_fma_f32 v[132:133], v[18:19], v[174:175], v[132:133]
	v_pk_fma_f32 v[134:135], v[18:19], v[194:195], v[134:135]
	v_add_f32_e32 v207, v146, v147
	v_pk_mul_f32 v[136:137], v[116:117], v[168:169] op_sel_hi:[0,1]
	v_add_f32_e32 v148, v132, v133
	v_cndmask_b32_e64 v208, v204, v205, s[10:11]
	v_add_f32_e32 v149, v134, v135
	v_pk_mul_f32 v[138:139], v[116:117], v[170:171] op_sel_hi:[0,1]
	v_cndmask_b32_e64 v209, v205, v204, s[10:11]
	v_add_f32_dpp v148, v148, v148 quad_perm:[1,0,3,2] row_mask:0xf bank_mask:0xf bound_ctrl:1
	v_add_f32_dpp v149, v149, v149 quad_perm:[1,0,3,2] row_mask:0xf bank_mask:0xf bound_ctrl:1
	v_cndmask_b32_e64 v210, v206, v207, s[10:11]
	v_pk_fma_f32 v[136:137], v[16:17], v[160:161], v[136:137]
	v_add_f32_dpp v148, v148, v148 quad_perm:[2,3,0,1] row_mask:0xf bank_mask:0xf bound_ctrl:1
	v_cndmask_b32_e64 v211, v207, v206, s[10:11]
	v_add_f32_dpp v149, v149, v149 quad_perm:[2,3,0,1] row_mask:0xf bank_mask:0xf bound_ctrl:1
	v_pk_fma_f32 v[138:139], v[18:19], v[162:163], v[138:139]
	v_add_f32_dpp v212, v209, v208 quad_perm:[1,0,3,2] row_mask:0xf bank_mask:0xf bound_ctrl:1
	v_add_f32_dpp v148, v148, v148 row_half_mirror row_mask:0xf bank_mask:0xf bound_ctrl:1
	v_add_f32_dpp v149, v149, v149 row_half_mirror row_mask:0xf bank_mask:0xf bound_ctrl:1
	v_add_f32_dpp v213, v211, v210 quad_perm:[1,0,3,2] row_mask:0xf bank_mask:0xf bound_ctrl:1
	ds_read_b128 v[44:47], v29 offset:23088
	ds_read_b128 v[64:67], v29 offset:24368
	ds_read_b128 v[40:43], v29 offset:23072
	ds_read2_b32 v[112:113], v122 offset0:120 offset1:140
	ds_read_b128 v[32:35], v29 offset:23040
	ds_read_b128 v[48:51], v29 offset:23104
	ds_read_b128 v[60:63], v29 offset:24352
	ds_read_b128 v[52:55], v29 offset:24320
	ds_read_b128 v[36:39], v29 offset:23056
	ds_read_b128 v[68:71], v29 offset:24384
	ds_read_b128 v[56:59], v29 offset:24336
	s_waitcnt lgkmcnt(11)
	v_pk_mul_f32 v[140:141], v[116:117], v[188:189] op_sel:[1,0] op_sel_hi:[1,1]
	v_cndmask_b32_e64 v214, v212, v213, s[14:15]
	v_add_f32_dpp v148, v148, v148 row_mirror row_mask:0xf bank_mask:0xf bound_ctrl:1
	v_add_f32_dpp v149, v149, v149 row_mirror row_mask:0xf bank_mask:0xf bound_ctrl:1
	v_cndmask_b32_e64 v215, v213, v212, s[14:15]
	v_pk_mul_f32 v[142:143], v[116:117], v[190:191] op_sel:[1,0] op_sel_hi:[1,1]
	v_fmac_f32_e32 v149, v116, v118
	v_add_f32_dpp v216, v215, v214 quad_perm:[2,3,0,1] row_mask:0xf bank_mask:0xf bound_ctrl:1
	v_pk_fma_f32 v[16:17], v[176:177], v[148:149], v[136:137] op_sel_hi:[1,0,1]
	v_pk_fma_f32 v[18:19], v[178:179], v[148:149], v[138:139] op_sel_hi:[1,0,1]
	v_add_f32_dpp v216, v216, v216 row_ror:8 row_mask:0xf bank_mask:0xf bound_ctrl:1
	v_pk_fma_f32 v[140:141], v[16:17], v[180:181], v[140:141]
	v_pk_mul_f32 v[144:145], v[16:17], v[164:165]
	v_add_f32_dpp v216, v216, v216 row_ror:4 row_mask:0xf bank_mask:0xf bound_ctrl:1
	v_pk_fma_f32 v[142:143], v[18:19], v[182:183], v[142:143]
	v_pk_fma_f32 v[144:145], v[18:19], v[166:167], v[144:145]
	v_cndmask_b32_e64 v28, v28, v216, s[44:45]
	v_pk_fma_f32 v[16:17], v[196:197], v[148:149], v[140:141] op_sel:[0,1,0] op_sel_hi:[1,1,1]
	v_pk_fma_f32 v[18:19], v[198:199], v[148:149], v[142:143] op_sel:[0,1,0] op_sel_hi:[1,1,1]
	v_add_co_u32_e32 v218, vcc, s59, v12
	v_pk_mul_f32 v[146:147], v[16:17], v[184:185]
	v_pk_fma_f32 v[146:147], v[18:19], v[186:187], v[146:147]
	s_nop 1
	v_addc_co_u32_e32 v219, vcc, 0, v13, vcc
	global_store_dword v[218:219], v28, off
	s_waitcnt lgkmcnt(6)
	v_pk_mul_f32 v[132:133], v[16:17], v[44:45]
	v_pk_mul_f32 v[134:135], v[16:17], v[64:65]
	v_add_f32_e32 v200, v144, v145
	v_pk_fma_f32 v[132:133], v[18:19], v[46:47], v[132:133]
	v_pk_fma_f32 v[134:135], v[18:19], v[66:67], v[134:135]
	v_add_f32_e32 v201, v146, v147
	v_pk_mul_f32 v[136:137], v[112:113], v[40:41] op_sel_hi:[0,1]
	v_add_f32_e32 v148, v132, v133
	v_add_f32_e32 v149, v134, v135
	v_pk_mul_f32 v[138:139], v[112:113], v[42:43] op_sel_hi:[0,1]
	v_add_f32_dpp v148, v148, v148 quad_perm:[1,0,3,2] row_mask:0xf bank_mask:0xf bound_ctrl:1
	v_add_f32_dpp v149, v149, v149 quad_perm:[1,0,3,2] row_mask:0xf bank_mask:0xf bound_ctrl:1
	v_pk_fma_f32 v[136:137], v[16:17], v[32:33], v[136:137]
	v_add_f32_dpp v148, v148, v148 quad_perm:[2,3,0,1] row_mask:0xf bank_mask:0xf bound_ctrl:1
	v_add_f32_dpp v149, v149, v149 quad_perm:[2,3,0,1] row_mask:0xf bank_mask:0xf bound_ctrl:1
	v_pk_fma_f32 v[138:139], v[18:19], v[34:35], v[138:139]
	v_add_f32_dpp v148, v148, v148 row_half_mirror row_mask:0xf bank_mask:0xf bound_ctrl:1
	v_add_f32_dpp v149, v149, v149 row_half_mirror row_mask:0xf bank_mask:0xf bound_ctrl:1
	ds_read_b128 v[84:87], v29 offset:25648
	ds_read_b128 v[104:107], v29 offset:26928
	ds_read_b128 v[80:83], v29 offset:25632
	ds_read2_b32 v[114:115], v122 offset0:160 offset1:180
	ds_read_b128 v[72:75], v29 offset:25600
	ds_read2_b32 v[120:121], v124 offset0:196 offset1:236
	ds_read_b128 v[88:91], v29 offset:25664
	ds_read_b128 v[100:103], v29 offset:26912
	ds_read_b128 v[92:95], v29 offset:26880
	ds_read_b128 v[76:79], v29 offset:25616
	ds_read_b128 v[108:111], v29 offset:26944
	ds_read_b128 v[96:99], v29 offset:26896
	s_waitcnt lgkmcnt(12)
	v_pk_mul_f32 v[140:141], v[112:113], v[60:61] op_sel:[1,0] op_sel_hi:[1,1]
	v_add_f32_dpp v148, v148, v148 row_mirror row_mask:0xf bank_mask:0xf bound_ctrl:1
	v_add_f32_dpp v149, v149, v149 row_mirror row_mask:0xf bank_mask:0xf bound_ctrl:1
	v_pk_mul_f32 v[142:143], v[112:113], v[62:63] op_sel:[1,0] op_sel_hi:[1,1]
	v_fmac_f32_e32 v149, v112, v119
	v_pk_fma_f32 v[16:17], v[48:49], v[148:149], v[136:137] op_sel_hi:[1,0,1]
	v_pk_fma_f32 v[18:19], v[50:51], v[148:149], v[138:139] op_sel_hi:[1,0,1]
	v_pk_fma_f32 v[140:141], v[16:17], v[52:53], v[140:141]
	v_pk_mul_f32 v[144:145], v[16:17], v[36:37]
	v_pk_fma_f32 v[142:143], v[18:19], v[54:55], v[142:143]
	v_pk_fma_f32 v[144:145], v[18:19], v[38:39], v[144:145]
	v_pk_fma_f32 v[16:17], v[68:69], v[148:149], v[140:141] op_sel:[0,1,0] op_sel_hi:[1,1,1]
	v_pk_fma_f32 v[18:19], v[70:71], v[148:149], v[142:143] op_sel:[0,1,0] op_sel_hi:[1,1,1]
	v_pk_mul_f32 v[146:147], v[16:17], v[56:57]
	v_pk_fma_f32 v[146:147], v[18:19], v[58:59], v[146:147]
	s_waitcnt lgkmcnt(7)
	v_pk_mul_f32 v[132:133], v[16:17], v[84:85]
	v_pk_mul_f32 v[134:135], v[16:17], v[104:105]
	v_add_f32_e32 v202, v144, v145
	v_pk_fma_f32 v[132:133], v[18:19], v[86:87], v[132:133]
	v_pk_fma_f32 v[134:135], v[18:19], v[106:107], v[134:135]
	v_add_f32_e32 v203, v146, v147
	v_pk_mul_f32 v[136:137], v[114:115], v[80:81] op_sel_hi:[0,1]
	v_add_f32_e32 v148, v132, v133
	v_cndmask_b32_e64 v208, v200, v201, s[10:11]
	v_add_f32_e32 v149, v134, v135
	v_pk_mul_f32 v[138:139], v[114:115], v[82:83] op_sel_hi:[0,1]
	v_cndmask_b32_e64 v209, v201, v200, s[10:11]
	v_add_f32_dpp v148, v148, v148 quad_perm:[1,0,3,2] row_mask:0xf bank_mask:0xf bound_ctrl:1
	v_add_f32_dpp v149, v149, v149 quad_perm:[1,0,3,2] row_mask:0xf bank_mask:0xf bound_ctrl:1
	v_cndmask_b32_e64 v210, v202, v203, s[10:11]
	v_pk_fma_f32 v[136:137], v[16:17], v[72:73], v[136:137]
	v_add_f32_dpp v148, v148, v148 quad_perm:[2,3,0,1] row_mask:0xf bank_mask:0xf bound_ctrl:1
	v_cndmask_b32_e64 v211, v203, v202, s[10:11]
	v_add_f32_dpp v149, v149, v149 quad_perm:[2,3,0,1] row_mask:0xf bank_mask:0xf bound_ctrl:1
	v_pk_fma_f32 v[138:139], v[18:19], v[74:75], v[138:139]
	v_add_f32_dpp v212, v209, v208 quad_perm:[1,0,3,2] row_mask:0xf bank_mask:0xf bound_ctrl:1
	v_add_f32_dpp v148, v148, v148 row_half_mirror row_mask:0xf bank_mask:0xf bound_ctrl:1
	v_add_f32_dpp v149, v149, v149 row_half_mirror row_mask:0xf bank_mask:0xf bound_ctrl:1
	v_add_f32_dpp v213, v211, v210 quad_perm:[1,0,3,2] row_mask:0xf bank_mask:0xf bound_ctrl:1
	ds_read_b128 v[172:175], v29 offset:28208
	ds_read_b128 v[192:195], v29 offset:29488
	ds_read_b128 v[168:171], v29 offset:28192
	ds_read2_b32 v[116:117], v122 offset0:200 offset1:220
	ds_read_b128 v[160:163], v29 offset:28160
	ds_read_b128 v[176:179], v29 offset:28224
	ds_read_b128 v[188:191], v29 offset:29472
	ds_read_b128 v[180:183], v29 offset:29440
	ds_read_b128 v[164:167], v29 offset:28176
	ds_read_b128 v[196:199], v29 offset:29504
	ds_read_b128 v[184:187], v29 offset:29456
	s_waitcnt lgkmcnt(11)
	v_pk_mul_f32 v[140:141], v[114:115], v[100:101] op_sel:[1,0] op_sel_hi:[1,1]
	v_cndmask_b32_e64 v214, v212, v213, s[14:15]
	v_add_f32_dpp v148, v148, v148 row_mirror row_mask:0xf bank_mask:0xf bound_ctrl:1
	v_add_f32_dpp v149, v149, v149 row_mirror row_mask:0xf bank_mask:0xf bound_ctrl:1
	v_cndmask_b32_e64 v215, v213, v212, s[14:15]
	v_pk_mul_f32 v[142:143], v[114:115], v[102:103] op_sel:[1,0] op_sel_hi:[1,1]
	v_fmac_f32_e32 v149, v114, v120
	v_add_f32_dpp v216, v215, v214 quad_perm:[2,3,0,1] row_mask:0xf bank_mask:0xf bound_ctrl:1
	v_pk_fma_f32 v[16:17], v[88:89], v[148:149], v[136:137] op_sel_hi:[1,0,1]
	v_pk_fma_f32 v[18:19], v[90:91], v[148:149], v[138:139] op_sel_hi:[1,0,1]
	v_add_f32_dpp v216, v216, v216 row_ror:8 row_mask:0xf bank_mask:0xf bound_ctrl:1
	v_pk_fma_f32 v[140:141], v[16:17], v[92:93], v[140:141]
	v_pk_mul_f32 v[144:145], v[16:17], v[76:77]
	v_add_f32_dpp v216, v216, v216 row_ror:4 row_mask:0xf bank_mask:0xf bound_ctrl:1
	v_pk_fma_f32 v[142:143], v[18:19], v[94:95], v[142:143]
	v_pk_fma_f32 v[144:145], v[18:19], v[78:79], v[144:145]
	v_cndmask_b32_e64 v28, v28, v216, s[34:35]
	v_pk_fma_f32 v[16:17], v[108:109], v[148:149], v[140:141] op_sel:[0,1,0] op_sel_hi:[1,1,1]
	v_pk_fma_f32 v[18:19], v[110:111], v[148:149], v[142:143] op_sel:[0,1,0] op_sel_hi:[1,1,1]
	v_pk_mul_f32 v[146:147], v[16:17], v[96:97]
	v_pk_fma_f32 v[146:147], v[18:19], v[98:99], v[146:147]
	s_waitcnt lgkmcnt(6)
	v_pk_mul_f32 v[132:133], v[16:17], v[172:173]
	v_pk_mul_f32 v[134:135], v[16:17], v[192:193]
	v_add_f32_e32 v204, v144, v145
	v_pk_fma_f32 v[132:133], v[18:19], v[174:175], v[132:133]
	v_pk_fma_f32 v[134:135], v[18:19], v[194:195], v[134:135]
	v_add_f32_e32 v205, v146, v147
	v_pk_mul_f32 v[136:137], v[116:117], v[168:169] op_sel_hi:[0,1]
	v_add_f32_e32 v148, v132, v133
	v_add_f32_e32 v149, v134, v135
	v_pk_mul_f32 v[138:139], v[116:117], v[170:171] op_sel_hi:[0,1]
	v_add_f32_dpp v148, v148, v148 quad_perm:[1,0,3,2] row_mask:0xf bank_mask:0xf bound_ctrl:1
	v_add_f32_dpp v149, v149, v149 quad_perm:[1,0,3,2] row_mask:0xf bank_mask:0xf bound_ctrl:1
	v_pk_fma_f32 v[136:137], v[16:17], v[160:161], v[136:137]
	v_add_f32_dpp v148, v148, v148 quad_perm:[2,3,0,1] row_mask:0xf bank_mask:0xf bound_ctrl:1
	v_add_f32_dpp v149, v149, v149 quad_perm:[2,3,0,1] row_mask:0xf bank_mask:0xf bound_ctrl:1
	v_pk_fma_f32 v[138:139], v[18:19], v[162:163], v[138:139]
	v_add_f32_dpp v148, v148, v148 row_half_mirror row_mask:0xf bank_mask:0xf bound_ctrl:1
	v_add_f32_dpp v149, v149, v149 row_half_mirror row_mask:0xf bank_mask:0xf bound_ctrl:1
	ds_read_b128 v[44:47], v29 offset:30768
	ds_read_b128 v[64:67], v29 offset:32048
	ds_read_b128 v[40:43], v29 offset:30752
	ds_read2_b32 v[112:113], v123 offset0:0 offset1:20
	ds_read_b128 v[32:35], v29 offset:30720
	ds_read2_b32 v[118:119], v125 offset0:36 offset1:76
	ds_read_b128 v[48:51], v29 offset:30784
	ds_read_b128 v[60:63], v29 offset:32032
	ds_read_b128 v[52:55], v29 offset:32000
	ds_read_b128 v[36:39], v29 offset:30736
	ds_read_b128 v[68:71], v29 offset:32064
	ds_read_b128 v[56:59], v29 offset:32016
	s_waitcnt lgkmcnt(12)
	v_pk_mul_f32 v[140:141], v[116:117], v[188:189] op_sel:[1,0] op_sel_hi:[1,1]
	v_add_f32_dpp v148, v148, v148 row_mirror row_mask:0xf bank_mask:0xf bound_ctrl:1
	v_add_f32_dpp v149, v149, v149 row_mirror row_mask:0xf bank_mask:0xf bound_ctrl:1
	v_pk_mul_f32 v[142:143], v[116:117], v[190:191] op_sel:[1,0] op_sel_hi:[1,1]
	v_fmac_f32_e32 v149, v116, v121
	v_pk_fma_f32 v[16:17], v[176:177], v[148:149], v[136:137] op_sel_hi:[1,0,1]
	v_pk_fma_f32 v[18:19], v[178:179], v[148:149], v[138:139] op_sel_hi:[1,0,1]
	v_pk_fma_f32 v[140:141], v[16:17], v[180:181], v[140:141]
	v_pk_mul_f32 v[144:145], v[16:17], v[164:165]
	v_pk_fma_f32 v[142:143], v[18:19], v[182:183], v[142:143]
	v_pk_fma_f32 v[144:145], v[18:19], v[166:167], v[144:145]
	v_pk_fma_f32 v[16:17], v[196:197], v[148:149], v[140:141] op_sel:[0,1,0] op_sel_hi:[1,1,1]
	v_pk_fma_f32 v[18:19], v[198:199], v[148:149], v[142:143] op_sel:[0,1,0] op_sel_hi:[1,1,1]
	v_pk_mul_f32 v[146:147], v[16:17], v[184:185]
	v_pk_fma_f32 v[146:147], v[18:19], v[186:187], v[146:147]
	s_waitcnt lgkmcnt(7)
	v_pk_mul_f32 v[132:133], v[16:17], v[44:45]
	v_pk_mul_f32 v[134:135], v[16:17], v[64:65]
	v_add_f32_e32 v206, v144, v145
	v_pk_fma_f32 v[132:133], v[18:19], v[46:47], v[132:133]
	v_pk_fma_f32 v[134:135], v[18:19], v[66:67], v[134:135]
	v_add_f32_e32 v207, v146, v147
	v_pk_mul_f32 v[136:137], v[112:113], v[40:41] op_sel_hi:[0,1]
	v_add_f32_e32 v148, v132, v133
	v_cndmask_b32_e64 v208, v204, v205, s[10:11]
	v_add_f32_e32 v149, v134, v135
	v_pk_mul_f32 v[138:139], v[112:113], v[42:43] op_sel_hi:[0,1]
	v_cndmask_b32_e64 v209, v205, v204, s[10:11]
	v_add_f32_dpp v148, v148, v148 quad_perm:[1,0,3,2] row_mask:0xf bank_mask:0xf bound_ctrl:1
	v_add_f32_dpp v149, v149, v149 quad_perm:[1,0,3,2] row_mask:0xf bank_mask:0xf bound_ctrl:1
	v_cndmask_b32_e64 v210, v206, v207, s[10:11]
	v_pk_fma_f32 v[136:137], v[16:17], v[32:33], v[136:137]
	v_add_f32_dpp v148, v148, v148 quad_perm:[2,3,0,1] row_mask:0xf bank_mask:0xf bound_ctrl:1
	v_cndmask_b32_e64 v211, v207, v206, s[10:11]
	v_add_f32_dpp v149, v149, v149 quad_perm:[2,3,0,1] row_mask:0xf bank_mask:0xf bound_ctrl:1
	v_pk_fma_f32 v[138:139], v[18:19], v[34:35], v[138:139]
	v_add_f32_dpp v212, v209, v208 quad_perm:[1,0,3,2] row_mask:0xf bank_mask:0xf bound_ctrl:1
	v_add_f32_dpp v148, v148, v148 row_half_mirror row_mask:0xf bank_mask:0xf bound_ctrl:1
	v_add_f32_dpp v149, v149, v149 row_half_mirror row_mask:0xf bank_mask:0xf bound_ctrl:1
	v_add_f32_dpp v213, v211, v210 quad_perm:[1,0,3,2] row_mask:0xf bank_mask:0xf bound_ctrl:1
	ds_read_b128 v[84:87], v29 offset:33328
	ds_read_b128 v[104:107], v29 offset:34608
	ds_read_b128 v[80:83], v29 offset:33312
	ds_read2_b32 v[114:115], v123 offset0:40 offset1:60
	ds_read_b128 v[72:75], v29 offset:33280
	ds_read_b128 v[88:91], v29 offset:33344
	ds_read_b128 v[100:103], v29 offset:34592
	ds_read_b128 v[92:95], v29 offset:34560
	ds_read_b128 v[76:79], v29 offset:33296
	ds_read_b128 v[108:111], v29 offset:34624
	ds_read_b128 v[96:99], v29 offset:34576
	s_waitcnt lgkmcnt(11)
	v_pk_mul_f32 v[140:141], v[112:113], v[60:61] op_sel:[1,0] op_sel_hi:[1,1]
	v_cndmask_b32_e64 v214, v212, v213, s[14:15]
	v_add_f32_dpp v148, v148, v148 row_mirror row_mask:0xf bank_mask:0xf bound_ctrl:1
	v_add_f32_dpp v149, v149, v149 row_mirror row_mask:0xf bank_mask:0xf bound_ctrl:1
	v_cndmask_b32_e64 v215, v213, v212, s[14:15]
	v_pk_mul_f32 v[142:143], v[112:113], v[62:63] op_sel:[1,0] op_sel_hi:[1,1]
	v_fmac_f32_e32 v149, v112, v118
	v_add_f32_dpp v216, v215, v214 quad_perm:[2,3,0,1] row_mask:0xf bank_mask:0xf bound_ctrl:1
	v_pk_fma_f32 v[16:17], v[48:49], v[148:149], v[136:137] op_sel_hi:[1,0,1]
	v_pk_fma_f32 v[18:19], v[50:51], v[148:149], v[138:139] op_sel_hi:[1,0,1]
	v_add_f32_dpp v216, v216, v216 row_ror:8 row_mask:0xf bank_mask:0xf bound_ctrl:1
	v_pk_fma_f32 v[140:141], v[16:17], v[52:53], v[140:141]
	v_pk_mul_f32 v[144:145], v[16:17], v[36:37]
	v_add_f32_dpp v216, v216, v216 row_ror:4 row_mask:0xf bank_mask:0xf bound_ctrl:1
	v_pk_fma_f32 v[142:143], v[18:19], v[54:55], v[142:143]
	v_pk_fma_f32 v[144:145], v[18:19], v[38:39], v[144:145]
	v_cndmask_b32_e64 v28, v28, v216, s[36:37]
	v_pk_fma_f32 v[16:17], v[68:69], v[148:149], v[140:141] op_sel:[0,1,0] op_sel_hi:[1,1,1]
	v_pk_fma_f32 v[18:19], v[70:71], v[148:149], v[142:143] op_sel:[0,1,0] op_sel_hi:[1,1,1]
	v_pk_mul_f32 v[146:147], v[16:17], v[56:57]
	v_pk_fma_f32 v[146:147], v[18:19], v[58:59], v[146:147]
	s_waitcnt lgkmcnt(6)
	v_pk_mul_f32 v[132:133], v[16:17], v[84:85]
	v_pk_mul_f32 v[134:135], v[16:17], v[104:105]
	v_add_f32_e32 v200, v144, v145
	v_pk_fma_f32 v[132:133], v[18:19], v[86:87], v[132:133]
	v_pk_fma_f32 v[134:135], v[18:19], v[106:107], v[134:135]
	v_add_f32_e32 v201, v146, v147
	v_pk_mul_f32 v[136:137], v[114:115], v[80:81] op_sel_hi:[0,1]
	v_add_f32_e32 v148, v132, v133
	v_add_f32_e32 v149, v134, v135
	v_pk_mul_f32 v[138:139], v[114:115], v[82:83] op_sel_hi:[0,1]
	v_add_f32_dpp v148, v148, v148 quad_perm:[1,0,3,2] row_mask:0xf bank_mask:0xf bound_ctrl:1
	v_add_f32_dpp v149, v149, v149 quad_perm:[1,0,3,2] row_mask:0xf bank_mask:0xf bound_ctrl:1
	v_pk_fma_f32 v[136:137], v[16:17], v[72:73], v[136:137]
	v_add_f32_dpp v148, v148, v148 quad_perm:[2,3,0,1] row_mask:0xf bank_mask:0xf bound_ctrl:1
	v_add_f32_dpp v149, v149, v149 quad_perm:[2,3,0,1] row_mask:0xf bank_mask:0xf bound_ctrl:1
	v_pk_fma_f32 v[138:139], v[18:19], v[74:75], v[138:139]
	v_add_f32_dpp v148, v148, v148 row_half_mirror row_mask:0xf bank_mask:0xf bound_ctrl:1
	v_add_f32_dpp v149, v149, v149 row_half_mirror row_mask:0xf bank_mask:0xf bound_ctrl:1
	ds_read_b128 v[172:175], v29 offset:35888
	ds_read_b128 v[192:195], v29 offset:37168
	ds_read_b128 v[168:171], v29 offset:35872
	ds_read2_b32 v[116:117], v123 offset0:80 offset1:100
	ds_read_b128 v[160:163], v29 offset:35840
	ds_read2_b32 v[120:121], v125 offset0:116 offset1:156
	ds_read_b128 v[176:179], v29 offset:35904
	ds_read_b128 v[188:191], v29 offset:37152
	ds_read_b128 v[180:183], v29 offset:37120
	ds_read_b128 v[164:167], v29 offset:35856
	ds_read_b128 v[196:199], v29 offset:37184
	ds_read_b128 v[184:187], v29 offset:37136
	s_waitcnt lgkmcnt(12)
	v_pk_mul_f32 v[140:141], v[114:115], v[100:101] op_sel:[1,0] op_sel_hi:[1,1]
	v_add_f32_dpp v148, v148, v148 row_mirror row_mask:0xf bank_mask:0xf bound_ctrl:1
	v_add_f32_dpp v149, v149, v149 row_mirror row_mask:0xf bank_mask:0xf bound_ctrl:1
	v_pk_mul_f32 v[142:143], v[114:115], v[102:103] op_sel:[1,0] op_sel_hi:[1,1]
	v_fmac_f32_e32 v149, v114, v119
	v_pk_fma_f32 v[16:17], v[88:89], v[148:149], v[136:137] op_sel_hi:[1,0,1]
	v_pk_fma_f32 v[18:19], v[90:91], v[148:149], v[138:139] op_sel_hi:[1,0,1]
	v_pk_fma_f32 v[140:141], v[16:17], v[92:93], v[140:141]
	v_pk_mul_f32 v[144:145], v[16:17], v[76:77]
	v_pk_fma_f32 v[142:143], v[18:19], v[94:95], v[142:143]
	v_pk_fma_f32 v[144:145], v[18:19], v[78:79], v[144:145]
	v_pk_fma_f32 v[16:17], v[108:109], v[148:149], v[140:141] op_sel:[0,1,0] op_sel_hi:[1,1,1]
	v_pk_fma_f32 v[18:19], v[110:111], v[148:149], v[142:143] op_sel:[0,1,0] op_sel_hi:[1,1,1]
	v_pk_mul_f32 v[146:147], v[16:17], v[96:97]
	v_pk_fma_f32 v[146:147], v[18:19], v[98:99], v[146:147]
	s_waitcnt lgkmcnt(7)
	v_pk_mul_f32 v[132:133], v[16:17], v[172:173]
	v_pk_mul_f32 v[134:135], v[16:17], v[192:193]
	v_add_f32_e32 v202, v144, v145
	v_pk_fma_f32 v[132:133], v[18:19], v[174:175], v[132:133]
	v_pk_fma_f32 v[134:135], v[18:19], v[194:195], v[134:135]
	v_add_f32_e32 v203, v146, v147
	v_pk_mul_f32 v[136:137], v[116:117], v[168:169] op_sel_hi:[0,1]
	v_add_f32_e32 v148, v132, v133
	v_cndmask_b32_e64 v208, v200, v201, s[10:11]
	v_add_f32_e32 v149, v134, v135
	v_pk_mul_f32 v[138:139], v[116:117], v[170:171] op_sel_hi:[0,1]
	v_cndmask_b32_e64 v209, v201, v200, s[10:11]
	v_add_f32_dpp v148, v148, v148 quad_perm:[1,0,3,2] row_mask:0xf bank_mask:0xf bound_ctrl:1
	v_add_f32_dpp v149, v149, v149 quad_perm:[1,0,3,2] row_mask:0xf bank_mask:0xf bound_ctrl:1
	v_cndmask_b32_e64 v210, v202, v203, s[10:11]
	v_pk_fma_f32 v[136:137], v[16:17], v[160:161], v[136:137]
	v_add_f32_dpp v148, v148, v148 quad_perm:[2,3,0,1] row_mask:0xf bank_mask:0xf bound_ctrl:1
	v_cndmask_b32_e64 v211, v203, v202, s[10:11]
	v_add_f32_dpp v149, v149, v149 quad_perm:[2,3,0,1] row_mask:0xf bank_mask:0xf bound_ctrl:1
	v_pk_fma_f32 v[138:139], v[18:19], v[162:163], v[138:139]
	v_add_f32_dpp v212, v209, v208 quad_perm:[1,0,3,2] row_mask:0xf bank_mask:0xf bound_ctrl:1
	v_add_f32_dpp v148, v148, v148 row_half_mirror row_mask:0xf bank_mask:0xf bound_ctrl:1
	v_add_f32_dpp v149, v149, v149 row_half_mirror row_mask:0xf bank_mask:0xf bound_ctrl:1
	v_add_f32_dpp v213, v211, v210 quad_perm:[1,0,3,2] row_mask:0xf bank_mask:0xf bound_ctrl:1
	ds_read_b128 v[44:47], v29 offset:38448
	ds_read_b128 v[64:67], v29 offset:39728
	ds_read_b128 v[40:43], v29 offset:38432
	ds_read2_b32 v[112:113], v123 offset0:120 offset1:140
	ds_read_b128 v[32:35], v29 offset:38400
	ds_read_b128 v[48:51], v29 offset:38464
	ds_read_b128 v[60:63], v29 offset:39712
	ds_read_b128 v[52:55], v29 offset:39680
	ds_read_b128 v[36:39], v29 offset:38416
	ds_read_b128 v[68:71], v29 offset:39744
	ds_read_b128 v[56:59], v29 offset:39696
	s_waitcnt lgkmcnt(11)
	v_pk_mul_f32 v[140:141], v[116:117], v[188:189] op_sel:[1,0] op_sel_hi:[1,1]
	v_cndmask_b32_e64 v214, v212, v213, s[14:15]
	v_add_f32_dpp v148, v148, v148 row_mirror row_mask:0xf bank_mask:0xf bound_ctrl:1
	v_add_f32_dpp v149, v149, v149 row_mirror row_mask:0xf bank_mask:0xf bound_ctrl:1
	v_cndmask_b32_e64 v215, v213, v212, s[14:15]
	v_pk_mul_f32 v[142:143], v[116:117], v[190:191] op_sel:[1,0] op_sel_hi:[1,1]
	v_fmac_f32_e32 v149, v116, v120
	v_add_f32_dpp v216, v215, v214 quad_perm:[2,3,0,1] row_mask:0xf bank_mask:0xf bound_ctrl:1
	v_pk_fma_f32 v[16:17], v[176:177], v[148:149], v[136:137] op_sel_hi:[1,0,1]
	v_pk_fma_f32 v[18:19], v[178:179], v[148:149], v[138:139] op_sel_hi:[1,0,1]
	v_add_f32_dpp v216, v216, v216 row_ror:8 row_mask:0xf bank_mask:0xf bound_ctrl:1
	v_pk_fma_f32 v[140:141], v[16:17], v[180:181], v[140:141]
	v_pk_mul_f32 v[144:145], v[16:17], v[164:165]
	v_add_f32_dpp v216, v216, v216 row_ror:4 row_mask:0xf bank_mask:0xf bound_ctrl:1
	v_pk_fma_f32 v[142:143], v[18:19], v[182:183], v[142:143]
	v_pk_fma_f32 v[144:145], v[18:19], v[166:167], v[144:145]
	v_cndmask_b32_e64 v28, v28, v216, s[42:43]
	v_pk_fma_f32 v[16:17], v[196:197], v[148:149], v[140:141] op_sel:[0,1,0] op_sel_hi:[1,1,1]
	v_pk_fma_f32 v[18:19], v[198:199], v[148:149], v[142:143] op_sel:[0,1,0] op_sel_hi:[1,1,1]
	v_pk_mul_f32 v[146:147], v[16:17], v[184:185]
	v_pk_fma_f32 v[146:147], v[18:19], v[186:187], v[146:147]
	s_waitcnt lgkmcnt(6)
	v_pk_mul_f32 v[132:133], v[16:17], v[44:45]
	v_pk_mul_f32 v[134:135], v[16:17], v[64:65]
	v_add_f32_e32 v204, v144, v145
	v_pk_fma_f32 v[132:133], v[18:19], v[46:47], v[132:133]
	v_pk_fma_f32 v[134:135], v[18:19], v[66:67], v[134:135]
	v_add_f32_e32 v205, v146, v147
	v_pk_mul_f32 v[136:137], v[112:113], v[40:41] op_sel_hi:[0,1]
	v_add_f32_e32 v148, v132, v133
	v_add_f32_e32 v149, v134, v135
	v_pk_mul_f32 v[138:139], v[112:113], v[42:43] op_sel_hi:[0,1]
	v_add_f32_dpp v148, v148, v148 quad_perm:[1,0,3,2] row_mask:0xf bank_mask:0xf bound_ctrl:1
	v_add_f32_dpp v149, v149, v149 quad_perm:[1,0,3,2] row_mask:0xf bank_mask:0xf bound_ctrl:1
	v_pk_fma_f32 v[136:137], v[16:17], v[32:33], v[136:137]
	v_add_f32_dpp v148, v148, v148 quad_perm:[2,3,0,1] row_mask:0xf bank_mask:0xf bound_ctrl:1
	v_add_f32_dpp v149, v149, v149 quad_perm:[2,3,0,1] row_mask:0xf bank_mask:0xf bound_ctrl:1
	v_pk_fma_f32 v[138:139], v[18:19], v[34:35], v[138:139]
	v_add_f32_dpp v148, v148, v148 row_half_mirror row_mask:0xf bank_mask:0xf bound_ctrl:1
	v_add_f32_dpp v149, v149, v149 row_half_mirror row_mask:0xf bank_mask:0xf bound_ctrl:1
	s_waitcnt lgkmcnt(0)
	v_pk_mul_f32 v[140:141], v[112:113], v[60:61] op_sel:[1,0] op_sel_hi:[1,1]
	v_add_f32_dpp v148, v148, v148 row_mirror row_mask:0xf bank_mask:0xf bound_ctrl:1
	v_add_f32_dpp v149, v149, v149 row_mirror row_mask:0xf bank_mask:0xf bound_ctrl:1
	v_pk_mul_f32 v[142:143], v[112:113], v[62:63] op_sel:[1,0] op_sel_hi:[1,1]
	v_fmac_f32_e32 v149, v112, v121
	v_pk_fma_f32 v[16:17], v[48:49], v[148:149], v[136:137] op_sel_hi:[1,0,1]
	v_pk_fma_f32 v[18:19], v[50:51], v[148:149], v[138:139] op_sel_hi:[1,0,1]
	v_pk_fma_f32 v[140:141], v[16:17], v[52:53], v[140:141]
	v_pk_mul_f32 v[144:145], v[16:17], v[36:37]
	v_pk_fma_f32 v[142:143], v[18:19], v[54:55], v[142:143]
	v_pk_fma_f32 v[144:145], v[18:19], v[38:39], v[144:145]
	v_pk_fma_f32 v[16:17], v[68:69], v[148:149], v[140:141] op_sel:[0,1,0] op_sel_hi:[1,1,1]
	v_pk_fma_f32 v[18:19], v[70:71], v[148:149], v[142:143] op_sel:[0,1,0] op_sel_hi:[1,1,1]
	v_pk_mul_f32 v[146:147], v[16:17], v[56:57]
	v_pk_fma_f32 v[146:147], v[18:19], v[58:59], v[146:147]

.LBB0_506:
	s_and_saveexec_b64 s[40:41], s[4:5]
	s_cbranch_execz .Lscan_flush_skip0
	v_add_f32_e32 v206, v144, v145
	v_add_f32_e32 v207, v146, v147
	v_cndmask_b32_e64 v208, v204, v205, s[10:11]
	v_cndmask_b32_e64 v209, v205, v204, s[10:11]
	v_cndmask_b32_e64 v210, v206, v207, s[10:11]
	v_cndmask_b32_e64 v211, v207, v206, s[10:11]
	v_add_f32_dpp v212, v209, v208 quad_perm:[1,0,3,2] row_mask:0xf bank_mask:0xf bound_ctrl:1
	s_nop 0
	v_add_f32_dpp v213, v211, v210 quad_perm:[1,0,3,2] row_mask:0xf bank_mask:0xf bound_ctrl:1
	v_cndmask_b32_e64 v214, v212, v213, s[14:15]
	v_cndmask_b32_e64 v215, v213, v212, s[14:15]
	s_nop 1
	v_add_f32_dpp v216, v215, v214 quad_perm:[2,3,0,1] row_mask:0xf bank_mask:0xf bound_ctrl:1
	s_nop 1
	v_add_f32_dpp v216, v216, v216 row_ror:8 row_mask:0xf bank_mask:0xf bound_ctrl:1
	s_nop 1
	v_add_f32_dpp v216, v216, v216 row_ror:4 row_mask:0xf bank_mask:0xf bound_ctrl:1
	v_cndmask_b32_e64 v28, v28, v216, s[44:45]
	v_add_co_u32_e32 v218, vcc, 0x4cfc000, v12
	s_nop 1
	v_addc_co_u32_e32 v219, vcc, 0, v13, vcc
	global_store_dword v[218:219], v28, off
.Lscan_flush_skip0:
	s_or_b64 exec, exec, s[40:41]
	s_setprio 0
	v_cmp_eq_u32_e32 vcc, 0, v154
	s_and_saveexec_b64 s[4:5], vcc
	s_cbranch_execz .LBB0_516
	s_add_u32 s6, s16, 0xa100
	s_addc_u32 s7, s17, 0
	s_mov_b32 s10, 0x400001
	v_mov_b32_e32 v0, 0
	s_branch .LBB0_509
